# norm_gif phase: the LDS copy of the gate weight columns is filled with all 64 loads per thread in flight (counted waits) instead of 16 load-wait-store rounds; on top of convert-loop pipelining, global
# speedup vs baseline: 1.0013x; 1.0013x over previous
.LBB0_797:
	s_add_u32 s48, s80, 0xe00000
	s_addc_u32 s49, s81, 0
	s_cmp_lt_i32 s62, 9
	s_cselect_b64 s[0:1], -1, 0
	s_cmp_gt_i32 s63, 8
	s_cselect_b64 s[2:3], -1, 0
	s_and_b64 s[0:1], s[0:1], s[2:3]
	s_andn2_b64 vcc, exec, s[0:1]
	s_cbranch_vccnz .LBB0_875
	v_mov_b32_e32 v0, v212
	s_mov_b32 s0, 0x8000
	s_nop 0
	v_cmp_gt_i32_e32 vcc, s0, v0
	s_and_saveexec_b64 s[0:1], vcc
	s_cbranch_execz .LBB0_810
	s_waitcnt lgkmcnt(0)
	v_and_b32_e32 v9, 15, v0
	v_lshrrev_b32_e32 v1, 4, v0
	v_lshl_add_u32 v8, v9, 13, 0
	v_lshl_add_u32 v10, v1, 2, v8
	v_mul_u32_u24_e32 v11, 0x8040, v1
	v_lshl_add_u32 v11, v9, 2, v11
	v_add_u32_e32 v11, 0x6000, v11
	s_mov_b64 s[2:3], s[70:71]
	global_load_dword v140, v11, s[2:3]
	s_add_u32 s2, s2, 0x100800
	s_addc_u32 s3, s3, 0
	global_load_dword v141, v11, s[2:3]
	s_add_u32 s2, s2, 0x100800
	s_addc_u32 s3, s3, 0
	global_load_dword v142, v11, s[2:3]
	s_add_u32 s2, s2, 0x100800
	s_addc_u32 s3, s3, 0
	global_load_dword v143, v11, s[2:3]
	s_add_u32 s2, s2, 0x100800
	s_addc_u32 s3, s3, 0
	global_load_dword v144, v11, s[2:3]
	s_add_u32 s2, s2, 0x100800
	s_addc_u32 s3, s3, 0
	global_load_dword v145, v11, s[2:3]
	s_add_u32 s2, s2, 0x100800
	s_addc_u32 s3, s3, 0
	global_load_dword v146, v11, s[2:3]
	s_add_u32 s2, s2, 0x100800
	s_addc_u32 s3, s3, 0
	global_load_dword v147, v11, s[2:3]
	s_add_u32 s2, s2, 0x100800
	s_addc_u32 s3, s3, 0
	global_load_dword v148, v11, s[2:3]
	s_add_u32 s2, s2, 0x100800
	s_addc_u32 s3, s3, 0
	global_load_dword v149, v11, s[2:3]
	s_add_u32 s2, s2, 0x100800
	s_addc_u32 s3, s3, 0
	global_load_dword v150, v11, s[2:3]
	s_add_u32 s2, s2, 0x100800
	s_addc_u32 s3, s3, 0
	global_load_dword v151, v11, s[2:3]
	s_add_u32 s2, s2, 0x100800
	s_addc_u32 s3, s3, 0
	global_load_dword v152, v11, s[2:3]
	s_add_u32 s2, s2, 0x100800
	s_addc_u32 s3, s3, 0
	global_load_dword v153, v11, s[2:3]
	s_add_u32 s2, s2, 0x100800
	s_addc_u32 s3, s3, 0
	global_load_dword v154, v11, s[2:3]
	s_add_u32 s2, s2, 0x100800
	s_addc_u32 s3, s3, 0
	global_load_dword v155, v11, s[2:3]
	s_add_u32 s2, s2, 0x100800
	s_addc_u32 s3, s3, 0
	global_load_dword v156, v11, s[2:3]
	s_add_u32 s2, s2, 0x100800
	s_addc_u32 s3, s3, 0
	global_load_dword v157, v11, s[2:3]
	s_add_u32 s2, s2, 0x100800
	s_addc_u32 s3, s3, 0
	global_load_dword v158, v11, s[2:3]
	s_add_u32 s2, s2, 0x100800
	s_addc_u32 s3, s3, 0
	global_load_dword v159, v11, s[2:3]
	s_add_u32 s2, s2, 0x100800
	s_addc_u32 s3, s3, 0
	global_load_dword v160, v11, s[2:3]
	s_add_u32 s2, s2, 0x100800
	s_addc_u32 s3, s3, 0
	global_load_dword v161, v11, s[2:3]
	s_add_u32 s2, s2, 0x100800
	s_addc_u32 s3, s3, 0
	global_load_dword v162, v11, s[2:3]
	s_add_u32 s2, s2, 0x100800
	s_addc_u32 s3, s3, 0
	global_load_dword v163, v11, s[2:3]
	s_add_u32 s2, s2, 0x100800
	s_addc_u32 s3, s3, 0
	global_load_dword v164, v11, s[2:3]
	s_add_u32 s2, s2, 0x100800
	s_addc_u32 s3, s3, 0
	global_load_dword v165, v11, s[2:3]
	s_add_u32 s2, s2, 0x100800
	s_addc_u32 s3, s3, 0
	global_load_dword v166, v11, s[2:3]
	s_add_u32 s2, s2, 0x100800
	s_addc_u32 s3, s3, 0
	global_load_dword v167, v11, s[2:3]
	s_add_u32 s2, s2, 0x100800
	s_addc_u32 s3, s3, 0
	global_load_dword v168, v11, s[2:3]
	s_add_u32 s2, s2, 0x100800
	s_addc_u32 s3, s3, 0
	global_load_dword v169, v11, s[2:3]
	s_add_u32 s2, s2, 0x100800
	s_addc_u32 s3, s3, 0
	global_load_dword v170, v11, s[2:3]
	s_add_u32 s2, s2, 0x100800
	s_addc_u32 s3, s3, 0
	global_load_dword v171, v11, s[2:3]
	s_add_u32 s2, s2, 0x100800
	s_addc_u32 s3, s3, 0
	global_load_dword v172, v11, s[2:3]
	s_add_u32 s2, s2, 0x100800
	s_addc_u32 s3, s3, 0
	global_load_dword v173, v11, s[2:3]
	s_add_u32 s2, s2, 0x100800
	s_addc_u32 s3, s3, 0
	global_load_dword v174, v11, s[2:3]
	s_add_u32 s2, s2, 0x100800
	s_addc_u32 s3, s3, 0
	global_load_dword v175, v11, s[2:3]
	s_add_u32 s2, s2, 0x100800
	s_addc_u32 s3, s3, 0
	global_load_dword v176, v11, s[2:3]
	s_add_u32 s2, s2, 0x100800
	s_addc_u32 s3, s3, 0
	global_load_dword v177, v11, s[2:3]
	s_add_u32 s2, s2, 0x100800
	s_addc_u32 s3, s3, 0
	global_load_dword v178, v11, s[2:3]
	s_add_u32 s2, s2, 0x100800
	s_addc_u32 s3, s3, 0
	global_load_dword v179, v11, s[2:3]
	s_add_u32 s2, s2, 0x100800
	s_addc_u32 s3, s3, 0
	global_load_dword v180, v11, s[2:3]
	s_add_u32 s2, s2, 0x100800
	s_addc_u32 s3, s3, 0
	global_load_dword v181, v11, s[2:3]
	s_add_u32 s2, s2, 0x100800
	s_addc_u32 s3, s3, 0
	global_load_dword v182, v11, s[2:3]
	s_add_u32 s2, s2, 0x100800
	s_addc_u32 s3, s3, 0
	global_load_dword v183, v11, s[2:3]
	s_add_u32 s2, s2, 0x100800
	s_addc_u32 s3, s3, 0
	global_load_dword v184, v11, s[2:3]
	s_add_u32 s2, s2, 0x100800
	s_addc_u32 s3, s3, 0
	global_load_dword v185, v11, s[2:3]
	s_add_u32 s2, s2, 0x100800
	s_addc_u32 s3, s3, 0
	global_load_dword v186, v11, s[2:3]
	s_add_u32 s2, s2, 0x100800
	s_addc_u32 s3, s3, 0
	global_load_dword v187, v11, s[2:3]
	s_add_u32 s2, s2, 0x100800
	s_addc_u32 s3, s3, 0
	global_load_dword v188, v11, s[2:3]
	s_add_u32 s2, s2, 0x100800
	s_addc_u32 s3, s3, 0
	global_load_dword v189, v11, s[2:3]
	s_add_u32 s2, s2, 0x100800
	s_addc_u32 s3, s3, 0
	global_load_dword v190, v11, s[2:3]
	s_add_u32 s2, s2, 0x100800
	s_addc_u32 s3, s3, 0
	global_load_dword v191, v11, s[2:3]
	s_add_u32 s2, s2, 0x100800
	s_addc_u32 s3, s3, 0
	global_load_dword v192, v11, s[2:3]
	s_add_u32 s2, s2, 0x100800
	s_addc_u32 s3, s3, 0
	global_load_dword v193, v11, s[2:3]
	s_add_u32 s2, s2, 0x100800
	s_addc_u32 s3, s3, 0
	global_load_dword v194, v11, s[2:3]
	s_add_u32 s2, s2, 0x100800
	s_addc_u32 s3, s3, 0
	global_load_dword v195, v11, s[2:3]
	s_add_u32 s2, s2, 0x100800
	s_addc_u32 s3, s3, 0
	global_load_dword v196, v11, s[2:3]
	s_add_u32 s2, s2, 0x100800
	s_addc_u32 s3, s3, 0
	global_load_dword v197, v11, s[2:3]
	s_add_u32 s2, s2, 0x100800
	s_addc_u32 s3, s3, 0
	global_load_dword v198, v11, s[2:3]
	s_add_u32 s2, s2, 0x100800
	s_addc_u32 s3, s3, 0
	global_load_dword v199, v11, s[2:3]
	s_add_u32 s2, s2, 0x100800
	s_addc_u32 s3, s3, 0
	global_load_dword v200, v11, s[2:3]
	s_add_u32 s2, s2, 0x100800
	s_addc_u32 s3, s3, 0
	global_load_dword v201, v11, s[2:3]
	s_add_u32 s2, s2, 0x100800
	s_addc_u32 s3, s3, 0
	global_load_dword v202, v11, s[2:3]
	s_add_u32 s2, s2, 0x100800
	s_addc_u32 s3, s3, 0
	global_load_dword v203, v11, s[2:3]
	s_waitcnt vmcnt(48)
	ds_write_b32 v10, v140
	ds_write_b32 v10, v141 offset:128
	ds_write_b32 v10, v142 offset:256
	ds_write_b32 v10, v143 offset:384
	ds_write_b32 v10, v144 offset:512
	ds_write_b32 v10, v145 offset:640
	ds_write_b32 v10, v146 offset:768
	ds_write_b32 v10, v147 offset:896
	ds_write_b32 v10, v148 offset:1024
	ds_write_b32 v10, v149 offset:1152
	ds_write_b32 v10, v150 offset:1280
	ds_write_b32 v10, v151 offset:1408
	ds_write_b32 v10, v152 offset:1536
	ds_write_b32 v10, v153 offset:1664
	ds_write_b32 v10, v154 offset:1792
	ds_write_b32 v10, v155 offset:1920
	s_waitcnt vmcnt(32)
	ds_write_b32 v10, v156 offset:2048
	ds_write_b32 v10, v157 offset:2176
	ds_write_b32 v10, v158 offset:2304
	ds_write_b32 v10, v159 offset:2432
	ds_write_b32 v10, v160 offset:2560
	ds_write_b32 v10, v161 offset:2688
	ds_write_b32 v10, v162 offset:2816
	ds_write_b32 v10, v163 offset:2944
	ds_write_b32 v10, v164 offset:3072
	ds_write_b32 v10, v165 offset:3200
	ds_write_b32 v10, v166 offset:3328
	ds_write_b32 v10, v167 offset:3456
	ds_write_b32 v10, v168 offset:3584
	ds_write_b32 v10, v169 offset:3712
	ds_write_b32 v10, v170 offset:3840
	ds_write_b32 v10, v171 offset:3968
	s_waitcnt vmcnt(16)
	ds_write_b32 v10, v172 offset:4096
	ds_write_b32 v10, v173 offset:4224
	ds_write_b32 v10, v174 offset:4352
	ds_write_b32 v10, v175 offset:4480
	ds_write_b32 v10, v176 offset:4608
	ds_write_b32 v10, v177 offset:4736
	ds_write_b32 v10, v178 offset:4864
	ds_write_b32 v10, v179 offset:4992
	ds_write_b32 v10, v180 offset:5120
	ds_write_b32 v10, v181 offset:5248
	ds_write_b32 v10, v182 offset:5376
	ds_write_b32 v10, v183 offset:5504
	ds_write_b32 v10, v184 offset:5632
	ds_write_b32 v10, v185 offset:5760
	ds_write_b32 v10, v186 offset:5888
	ds_write_b32 v10, v187 offset:6016
	s_waitcnt vmcnt(0)
	ds_write_b32 v10, v188 offset:6144
	ds_write_b32 v10, v189 offset:6272
	ds_write_b32 v10, v190 offset:6400
	ds_write_b32 v10, v191 offset:6528
	ds_write_b32 v10, v192 offset:6656
	ds_write_b32 v10, v193 offset:6784
	ds_write_b32 v10, v194 offset:6912
	ds_write_b32 v10, v195 offset:7040
	ds_write_b32 v10, v196 offset:7168
	ds_write_b32 v10, v197 offset:7296
	ds_write_b32 v10, v198 offset:7424
	ds_write_b32 v10, v199 offset:7552
	ds_write_b32 v10, v200 offset:7680
	ds_write_b32 v10, v201 offset:7808
	ds_write_b32 v10, v202 offset:7936
	ds_write_b32 v10, v203 offset:8064
